# v26 plus segment-descriptor stepping and the G1 epilogue arithmetic trims (rsqrt guard, rope partner select) stacked
# speedup vs baseline: 1.0056x; 1.0056x over previous
; #define LOAD_PARAMS() KParams kq_ = (KParams)__builtin_amdgcn_kernarg_segment_ptr(); asm volatile("" : "+s"(kq_)); const Params p = *kq_
; template <int CT>
; __global__ void __launch_bounds__(NTHREADS) mega_kernel(Params p) {
;     ...
; #pragma unroll 1
;   for (int ph = 0; ph < nph; ++ph) {
;     run_phase<CT>(ph);
;     if (ph + 1 < nph) {
;       LOAD_PARAMS();
;       xcd_barrier((unsigned*)(p.ws + WS<CT>::bar), x, nloc, nx, k);
;       ++k;
;     }
;   }
; }
.LBB0_726:
	s_endpgm
	s_nop 0
	s_nop 0
	s_nop 0
	s_nop 0
	s_nop 0
	s_nop 0
	s_nop 0
	s_nop 0
	s_nop 0
	s_nop 0
	s_nop 0
	s_nop 0
	s_nop 0
	s_nop 0
	s_nop 0
	s_nop 0
	s_nop 0
	s_nop 0
	s_nop 0
	s_nop 0
	s_nop 0
	s_nop 0
	s_nop 0
	s_endpgm
